# cand D + prompt-prepass group reduction: the 4 LDS reads of the cross-wave sums issued together
# speedup vs baseline: 1.0238x; 1.0048x over previous
.LBB0_806:
	s_or_b64 exec, exec, s[38:39]
	s_waitcnt lgkmcnt(0)
	s_barrier
	s_and_saveexec_b64 s[38:39], s[36:37]
	s_cbranch_execz .LBB0_808
	ds_read2_b32 v[134:135], v206 offset1:16
	ds_read2_b32 v[246:247], v206 offset0:32 offset1:48
	ds_read2_b32 v[248:249], v206 offset0:64 offset1:80
	ds_read2_b32 v[250:251], v206 offset0:96 offset1:112
	s_waitcnt lgkmcnt(3)
	v_add_f32_e32 v134, 0, v134
	v_add_f32_e32 v136, v134, v135
	s_waitcnt lgkmcnt(2)
	v_add_f32_e32 v134, v136, v246
	v_add_f32_e32 v136, v134, v247
	s_waitcnt lgkmcnt(1)
	v_add_f32_e32 v134, v136, v248
	v_add_f32_e32 v136, v134, v249
	s_waitcnt lgkmcnt(0)
	v_add_f32_e32 v134, v136, v250
	v_add_f32_e32 v134, v134, v251
	ds_write_b32 v207, v134
